# v11 plus: prompt SSM item runs waves 0-3 at static priority 1 (reset at item end)
# baseline (speedup 1.0000x reference)
; template <bool SAMPLE>
; __device__ __forceinline__ void ssm_item(kp_t kp, LAS unsigned char* lds, int l, int item, const bf16_t* Z, float* YM, int tid, int lane, int wave) {
;     ...
;     __syncthreads();
; __global__ void __launch_bounds__(512, 2) fwd(Args a_unused) {
;     ...
;             for (int it = bid; it < 1280; it += G) {
;                 int t2 = tid; asm volatile("" : "+v"(t2));
;                 const int ln2 = t2 & 63, wv2 = __builtin_amdgcn_readfirstlane(t2 >> 6);
;                 if (it < 256) ssm_item<false>(kp, lds, l, it, Z, YM, t2, ln2, wv2);
;                 else if (it < 512) attn_prompt_item(kp, lds, l, it - 256, Z, YM, t2, ln2, wv2);
;                 else if (it < 1024) attn_sample_item(kp, lds, l, it - 512, Z, YM, t2);
;                 else ssm_item<true>(kp, lds, l, it - 1024, Z, YM, t2, ln2, wv2);
;             }
.LBB0_29:
	s_and_b64 vcc, exec, s[2:3]
	s_cbranch_vccz .LBB0_109
	v_readlane_b32 s0, v251, 9
	v_readlane_b32 s1, v251, 10
	s_andn2_b64 vcc, exec, s[0:1]
	s_cbranch_vccnz .LBB0_108
	s_add_u32 s0, s62, 0xb800000
	s_addc_u32 s1, s63, 0
	v_writelane_b32 v253, s0, 28
	v_readlane_b32 s30, v251, 5
	s_nop 0
	v_writelane_b32 v253, s1, 29
	s_add_u32 s0, s62, 0x10d00000
	s_addc_u32 s1, s63, 0
	v_writelane_b32 v253, s0, 30
	s_nop 1
	v_writelane_b32 v253, s1, 31
	s_nop 0
	v_readlane_b32 s2, v253, 12
	v_readlane_b32 s3, v253, 13
	s_and_b64 s[0:1], s[2:3], exec
	s_cselect_b32 s0, 64, 0
	v_writelane_b32 v253, s0, 32
	s_cselect_b32 s0, 0x80, 0
	v_writelane_b32 v253, s0, 33
	s_add_u32 s0, s60, 0x4640000
	v_writelane_b32 v253, s0, 34
	s_addc_u32 s0, s61, 0
	v_writelane_b32 v253, s0, 35
	s_add_u32 s0, s60, 0x6640000
	v_writelane_b32 v253, s0, 36
	s_addc_u32 s0, s61, 0
	v_writelane_b32 v253, s0, 37
	s_and_b64 s[0:1], s[2:3], exec
	s_cselect_b32 s0, 16, 0
	v_writelane_b32 v253, s0, 38
	s_cselect_b32 s0, 4, 0
	v_writelane_b32 v253, s0, 39
	s_add_u32 s0, s60, 0x4400000
	s_addc_u32 s1, s61, 0
	v_writelane_b32 v253, s0, 40
	s_nop 1
	v_writelane_b32 v253, s1, 41
	s_add_u32 s0, s60, 0x4500000
	s_addc_u32 s1, s61, 0
	v_writelane_b32 v253, s0, 42
	s_nop 1
	v_writelane_b32 v253, s1, 43
	s_add_u32 s0, s62, 0x10d01080
	s_addc_u32 s1, s63, 0
	v_writelane_b32 v253, s0, 44
	s_nop 1
	v_writelane_b32 v253, s1, 45
	s_add_u32 s0, s62, 0xb8a0000
	s_addc_u32 s1, s63, 0
	v_writelane_b32 v253, s0, 46
	s_nop 1
	v_writelane_b32 v253, s1, 47
	v_readlane_b32 s0, v251, 19
	s_mov_b32 s29, s0
	s_mov_b32 s31, s0
	v_writelane_b32 v253, s0, 48
	v_writelane_b32 v253, s58, 49
	s_nop 1
	v_writelane_b32 v253, s59, 50
	s_branch .LBB0_34
.LBB0_32:
	s_barrier
	s_setprio 0
.LBB0_33:
	v_readlane_b32 s0, v252, 42
	v_readlane_b32 s1, v252, 43
	v_readlane_b32 s1, v253, 48
	s_add_i32 s31, s31, s0
	s_add_i32 s30, s30, s0
	s_add_i32 s29, s29, s0
	s_add_i32 s1, s1, s0
	v_writelane_b32 v253, s1, 48
	s_cmpk_gt_i32 s31, 0x4ff
	s_waitcnt lgkmcnt(0)
	s_cbranch_scc1 .LBB0_108

; __device__ __forceinline__ void ssm_lane_math(const SsmRaw& r, float& lr, float& li, float (&bre)[16], float (&bim)[16]) {
;     const float Are = r.Are, Aim = r.Aim;
;     const float dt = expf(r.ldt);
;     const float er = expf(Are * dt);
;     const float ang = Aim * dt;
;     lr = er * cosf(ang); li = er * sinf(ang);
;     const float den = Are * Are + Aim * Aim, nr = lr - 1.0f, ni = li;
;     const float cr = (nr * Are + ni * Aim) / den, ci = (ni * Are - nr * Aim) / den;
; #pragma unroll
;     for (int q = 0; q < 4; ++q)
; #pragma unroll
;         for (int e = 0; e < 4; ++e) { bre[4 * q + e] = cr * r.br[q][e] - ci * r.bi[q][e]; bim[4 * q + e] = cr * r.bi[q][e] + ci * r.br[q][e]; }
.LBB0_99:
	s_or_b64 exec, exec, s[0:1]
	v_mul_f32_e32 v0, v72, v0
	v_mul_f32_e32 v71, 0x3fb8aa3b, v0
	s_mov_b32 s0, 0x3fb8aa3b
	v_fma_f32 v74, v0, s0, -v71
	v_rndne_f32_e32 v77, v71
	v_fmac_f32_e32 v74, 0x32a5705f, v0
	v_sub_f32_e32 v71, v71, v77
	v_add_f32_e32 v71, v71, v74
	v_cvt_i32_f32_e32 v74, v77
	v_exp_f32_e32 v71, v71
	s_mov_b32 s0, 0xc2ce8ed0
	v_cmp_ngt_f32_e32 vcc, s0, v0
	s_mov_b32 s0, 0x42b17218
	v_ldexp_f32 v71, v71, v74
	v_cndmask_b32_e32 v71, 0, v71, vcc
	v_cmp_nlt_f32_e32 vcc, s0, v0
	v_mul_f32_e32 v0, v68, v68
	s_brev_b32 s0, 1
	v_cndmask_b32_e32 v77, v192, v71, vcc
	v_fmamk_f32 v71, v0, 0xb94c1982, v181
	v_fmaak_f32 v71, v0, v71, 0xbe2aaa9d
	v_mul_f32_e32 v71, v0, v71
	v_fmac_f32_e32 v68, v68, v71
	v_fmamk_f32 v71, v0, 0x37d75334, v182
	v_fmaak_f32 v71, v0, v71, 0x3d2aabf7
	v_fmaak_f32 v71, v0, v71, 0xbf000004
	v_fma_f32 v0, v0, v71, 1.0
	v_and_b32_e32 v71, 1, v1
	v_cmp_eq_u32_e32 vcc, 0, v71
	v_mul_f32_e32 v71, v76, v76
	v_fmamk_f32 v74, v71, 0xb94c1982, v181
	v_fmaak_f32 v74, v71, v74, 0xbe2aaa9d
	v_mul_f32_e32 v74, v71, v74
	v_fmac_f32_e32 v76, v76, v74
	v_fmamk_f32 v74, v71, 0x37d75334, v182
	v_cndmask_b32_e64 v0, -v68, v0, vcc
	v_lshlrev_b32_e32 v1, 30, v1
	v_fmaak_f32 v74, v71, v74, 0x3d2aabf7
	v_bitop3_b32 v0, v1, v0, s0 bitop3:0x6c
	s_movk_i32 s0, 0x1f8
	v_fmaak_f32 v74, v71, v74, 0xbf000004
	v_cmp_class_f32_e64 vcc, v69, s0
	v_readlane_b32 s0, v253, 48
	v_fma_f32 v71, v71, v74, 1.0
	v_and_b32_e32 v74, 1, v75
	s_and_b32 s4, s0, 63
	v_cmp_eq_u32_e64 s[0:1], 0, v74
	v_lshlrev_b32_e32 v74, 30, v75
	v_and_b32_e32 v74, 0x80000000, v74
	v_xor_b32_e32 v69, v70, v69
	v_cndmask_b32_e64 v71, v71, v76, s[0:1]
	v_xor_b32_e32 v69, v69, v74
	v_xor_b32_e32 v69, v69, v71
	v_cndmask_b32_e32 v78, v195, v0, vcc
	v_cndmask_b32_e32 v69, v195, v69, vcc
	v_mul_f32_e32 v71, v77, v69
	v_fma_f32 v70, v77, v78, -1.0
	v_mov_b32_e32 v76, v73
	v_mul_f32_e32 v68, v77, v78
	v_pk_mul_f32 v[74:75], v[72:73], v[72:73]
	v_pk_mul_f32 v[76:77], v[76:77], v[70:71] op_sel:[0,1] op_sel_hi:[0,0]
	v_pk_fma_f32 v[78:79], v[72:73], v[70:71], v[76:77] op_sel_hi:[0,1,1] neg_lo:[0,0,1] neg_hi:[0,0,1]
	v_pk_add_f32 v[74:75], v[74:75], v[74:75] op_sel:[0,1] op_sel_hi:[0,1]
	v_div_scale_f32 v69, s[0:1], v75, v75, v79
	v_rcp_f32_e32 v78, v69
	v_pk_fma_f32 v[72:73], v[72:73], v[70:71], v[76:77]
	s_waitcnt vmcnt(18)
	v_xor_b32_e32 v20, 0x80000000, v20
	v_cvt_pk_bf16_f32 v16, v16, v20
	v_fma_f32 v70, -v69, v78, 1.0
	v_fmac_f32_e32 v78, v70, v78
	v_div_scale_f32 v70, vcc, v79, v75, v79
	v_mul_f32_e32 v73, v70, v78
	v_fma_f32 v76, -v69, v73, v70
	v_fmac_f32_e32 v73, v76, v78
	v_fma_f32 v69, -v69, v73, v70
	v_div_scale_f32 v70, s[0:1], v74, v74, v72
	v_rcp_f32_e32 v76, v70
	v_div_fmas_f32 v69, v69, v78, v73
	v_div_fixup_f32 v75, v69, v75, v79
	v_xor_b32_e32 v20, 0x80000000, v21
	v_fma_f32 v69, -v70, v76, 1.0
	v_fmac_f32_e32 v76, v69, v76
	v_div_scale_f32 v69, vcc, v72, v74, v72
	v_mul_f32_e32 v73, v69, v76
	v_fma_f32 v77, -v70, v73, v69
	v_fmac_f32_e32 v73, v77, v76
	v_fma_f32 v69, -v70, v73, v69
	v_div_fmas_f32 v69, v69, v76, v73
	v_div_fixup_f32 v74, v69, v74, v72
	v_pk_mul_f32 v[76:77], v[64:65], v[74:75] op_sel:[0,1] op_sel_hi:[0,0]
	v_pk_fma_f32 v[72:73], v[60:61], v[74:75], v[76:77] neg_lo:[0,0,1] neg_hi:[0,0,1]
	v_pk_fma_f32 v[76:77], v[60:61], v[74:75], v[76:77] op_sel_hi:[0,1,1]
	v_mov_b32_e32 v73, v77
	v_pk_mul_f32 v[76:77], v[64:65], v[74:75] op_sel:[1,1] op_sel_hi:[1,0]
	v_mov_b32_e32 v70, v63
	v_pk_fma_f32 v[64:65], v[60:61], v[74:75], v[76:77] op_sel:[1,0,0] neg_lo:[0,0,1] neg_hi:[0,0,1]
	v_pk_fma_f32 v[60:61], v[60:61], v[74:75], v[76:77] op_sel:[1,0,0]
	v_pk_mul_f32 v[76:77], v[66:67], v[74:75] op_sel:[0,1] op_sel_hi:[0,0]
	v_mov_b32_e32 v65, v61
	v_pk_fma_f32 v[60:61], v[62:63], v[74:75], v[76:77] neg_lo:[0,0,1] neg_hi:[0,0,1]
	v_pk_fma_f32 v[76:77], v[62:63], v[74:75], v[76:77] op_sel_hi:[0,1,1]
	v_mov_b32_e32 v62, v67
	v_pk_mul_f32 v[66:67], v[62:63], v[74:75] op_sel:[0,1] op_sel_hi:[0,0]
	v_mov_b32_e32 v61, v77
	v_pk_fma_f32 v[62:63], v[70:71], v[74:75], v[66:67] op_sel_hi:[0,1,1] neg_lo:[0,0,1] neg_hi:[0,0,1]
	v_pk_fma_f32 v[66:67], v[70:71], v[74:75], v[66:67] op_sel_hi:[0,1,1]
	v_pk_mul_f32 v[76:77], v[56:57], v[74:75] op_sel:[0,1] op_sel_hi:[0,0]
	v_mov_b32_e32 v63, v67
	v_pk_fma_f32 v[66:67], v[52:53], v[74:75], v[76:77] neg_lo:[0,0,1] neg_hi:[0,0,1]
	v_pk_fma_f32 v[76:77], v[52:53], v[74:75], v[76:77] op_sel_hi:[0,1,1]
	v_mov_b32_e32 v52, v57
	v_pk_mul_f32 v[56:57], v[52:53], v[74:75] op_sel:[0,1] op_sel_hi:[0,0]
	v_mov_b32_e32 v70, v53
	v_mov_b32_e32 v67, v77
	v_pk_fma_f32 v[52:53], v[70:71], v[74:75], v[56:57] op_sel_hi:[0,1,1] neg_lo:[0,0,1] neg_hi:[0,0,1]
	v_pk_fma_f32 v[56:57], v[70:71], v[74:75], v[56:57] op_sel_hi:[0,1,1]
	v_pk_mul_f32 v[76:77], v[58:59], v[74:75] op_sel:[0,1] op_sel_hi:[0,0]
	v_mov_b32_e32 v53, v57
	v_pk_fma_f32 v[56:57], v[54:55], v[74:75], v[76:77] neg_lo:[0,0,1] neg_hi:[0,0,1]
	v_pk_fma_f32 v[76:77], v[54:55], v[74:75], v[76:77] op_sel_hi:[0,1,1]
	v_mov_b32_e32 v54, v59
	v_pk_mul_f32 v[58:59], v[54:55], v[74:75] op_sel:[0,1] op_sel_hi:[0,0]
	v_mov_b32_e32 v70, v55
	v_mov_b32_e32 v57, v77
	v_pk_fma_f32 v[54:55], v[70:71], v[74:75], v[58:59] op_sel_hi:[0,1,1] neg_lo:[0,0,1] neg_hi:[0,0,1]
	v_pk_fma_f32 v[58:59], v[70:71], v[74:75], v[58:59] op_sel_hi:[0,1,1]
	v_pk_mul_f32 v[76:77], v[48:49], v[74:75] op_sel:[0,1] op_sel_hi:[0,0]
	v_mov_b32_e32 v55, v59
	v_pk_fma_f32 v[58:59], v[44:45], v[74:75], v[76:77] neg_lo:[0,0,1] neg_hi:[0,0,1]
	v_pk_fma_f32 v[76:77], v[44:45], v[74:75], v[76:77] op_sel_hi:[0,1,1]
	v_mov_b32_e32 v44, v49
	v_pk_mul_f32 v[48:49], v[44:45], v[74:75] op_sel:[0,1] op_sel_hi:[0,0]
	v_mov_b32_e32 v70, v45
; __device__ __forceinline__ unsigned cvt_pk_bf16(float lo, float hi) { unsigned r; asm("v_cvt_pk_bf16_f32 %0, %1, %2" : "=v"(r) : "v"(lo), "v"(hi)); return r; }
; template <bool SAMPLE>
; __device__ __forceinline__ void ssm_item(kp_t kp, LAS unsigned char* lds, int l, int item, const bf16_t* Z, float* YM, int tid, int lane, int wave) {
;     ...
;     float lr, li, bre[16], bim[16];
;     ssm_lane_math(raw, lr, li, bre, bim);
;     f32x2 B2[16];
; #pragma unroll
;     for (int c = 0; c < 16; ++c) B2[c] = (f32x2){bre[c], bim[c]};
;     f32x2 pw[16];
;     { float pr = lr, pi = li;
; #pragma unroll
;       for (int tt = 0; tt < 16; ++tt) { pw[tt] = (f32x2){pr, pi}; const float npr = pr * lr - pi * li; pi = pr * li + pi * lr; pr = npr; } }
;     const float l16r = pw[15].x, l16i = pw[15].y;
;     bf16x8 cf[4];
;     {
; #pragma unroll
;       for (int ks = 0; ks < 4; ++ks) { const f32x4 cr = craw[ks], ci = ciraw[ks];
;           u32x4 w; w.x = cvt_pk_bf16(cr[0], -ci[0]); w.y = cvt_pk_bf16(cr[1], -ci[1]); w.z = cvt_pk_bf16(cr[2], -ci[2]); w.w = cvt_pk_bf16(cr[3], -ci[3]);
;           cf[ks] = __builtin_bit_cast(bf16x8, w); } }
	v_mov_b32_e32 v59, v77
	v_pk_fma_f32 v[44:45], v[70:71], v[74:75], v[48:49] op_sel_hi:[0,1,1] neg_lo:[0,0,1] neg_hi:[0,0,1]
	v_pk_fma_f32 v[48:49], v[70:71], v[74:75], v[48:49] op_sel_hi:[0,1,1]
	v_pk_mul_f32 v[76:77], v[50:51], v[74:75] op_sel:[0,1] op_sel_hi:[0,0]
	v_mov_b32_e32 v45, v49
	v_pk_fma_f32 v[48:49], v[46:47], v[74:75], v[76:77] neg_lo:[0,0,1] neg_hi:[0,0,1]
	v_pk_fma_f32 v[76:77], v[46:47], v[74:75], v[76:77] op_sel_hi:[0,1,1]
	v_mov_b32_e32 v46, v51
	v_pk_mul_f32 v[50:51], v[46:47], v[74:75] op_sel:[0,1] op_sel_hi:[0,0]
	v_mov_b32_e32 v70, v47
	v_mov_b32_e32 v49, v77
	v_pk_fma_f32 v[46:47], v[70:71], v[74:75], v[50:51] op_sel_hi:[0,1,1] neg_lo:[0,0,1] neg_hi:[0,0,1]
	v_pk_fma_f32 v[50:51], v[70:71], v[74:75], v[50:51] op_sel_hi:[0,1,1]
	v_pk_mul_f32 v[76:77], v[40:41], v[74:75] op_sel:[0,1] op_sel_hi:[0,0]
	v_mov_b32_e32 v47, v51
	v_pk_fma_f32 v[50:51], v[36:37], v[74:75], v[76:77] neg_lo:[0,0,1] neg_hi:[0,0,1]
	v_pk_fma_f32 v[76:77], v[36:37], v[74:75], v[76:77] op_sel_hi:[0,1,1]
	v_mov_b32_e32 v36, v41
	v_pk_mul_f32 v[40:41], v[36:37], v[74:75] op_sel:[0,1] op_sel_hi:[0,0]
	v_mov_b32_e32 v70, v37
	v_mov_b32_e32 v51, v77
	v_pk_fma_f32 v[36:37], v[70:71], v[74:75], v[40:41] op_sel_hi:[0,1,1] neg_lo:[0,0,1] neg_hi:[0,0,1]
	v_pk_fma_f32 v[40:41], v[70:71], v[74:75], v[40:41] op_sel_hi:[0,1,1]
	v_pk_mul_f32 v[76:77], v[42:43], v[74:75] op_sel:[0,1] op_sel_hi:[0,0]
	v_mov_b32_e32 v37, v41
	v_pk_fma_f32 v[40:41], v[38:39], v[74:75], v[76:77] neg_lo:[0,0,1] neg_hi:[0,0,1]
	v_pk_fma_f32 v[76:77], v[38:39], v[74:75], v[76:77] op_sel_hi:[0,1,1]
	v_mov_b32_e32 v38, v43
	v_pk_mul_f32 v[42:43], v[38:39], v[74:75] op_sel:[0,1] op_sel_hi:[0,0]
	v_mov_b32_e32 v70, v39
	v_mov_b32_e32 v69, v71
	v_pk_fma_f32 v[38:39], v[70:71], v[74:75], v[42:43] op_sel_hi:[0,1,1] neg_lo:[0,0,1] neg_hi:[0,0,1]
	v_pk_fma_f32 v[42:43], v[70:71], v[74:75], v[42:43] op_sel_hi:[0,1,1]
	v_pk_mul_f32 v[74:75], v[68:69], v[68:69] op_sel:[1,1] op_sel_hi:[0,1]
	v_pk_fma_f32 v[112:113], v[68:69], v[68:69], v[74:75] op_sel_hi:[0,1,1] neg_lo:[0,0,1] neg_hi:[0,0,1]
	v_pk_fma_f32 v[114:115], v[68:69], v[68:69], v[74:75] op_sel_hi:[0,1,1]
	v_mov_b32_e32 v41, v77
	v_pk_mov_b32 v[76:77], v[114:115], v[112:113] op_sel:[1,0]
	v_mov_b32_e32 v74, v112
	v_mov_b32_e32 v75, v115
	v_pk_mul_f32 v[76:77], v[68:69], v[76:77] op_sel:[1,0]
	v_mov_b32_e32 v70, v71
	v_pk_fma_f32 v[116:117], v[68:69], v[74:75], v[76:77] op_sel_hi:[0,1,1] neg_lo:[0,0,1] neg_hi:[0,0,1]
	v_pk_fma_f32 v[118:119], v[68:69], v[74:75], v[76:77] op_sel_hi:[0,1,1]
	v_pk_mov_b32 v[78:79], v[118:119], v[116:117] op_sel:[1,0]
	v_mov_b32_e32 v76, v116
	v_mov_b32_e32 v77, v119
	v_pk_mul_f32 v[78:79], v[68:69], v[78:79] op_sel:[1,0]
	v_cvt_pk_bf16_f32 v17, v17, v20
	v_xor_b32_e32 v20, 0x80000000, v22
	v_pk_fma_f32 v[120:121], v[68:69], v[76:77], v[78:79] op_sel_hi:[0,1,1] neg_lo:[0,0,1] neg_hi:[0,0,1]
	v_pk_fma_f32 v[122:123], v[68:69], v[76:77], v[78:79] op_sel_hi:[0,1,1]
	v_pk_mov_b32 v[80:81], v[122:123], v[120:121] op_sel:[1,0]
	v_mov_b32_e32 v78, v120
	v_mov_b32_e32 v79, v123
	v_pk_mul_f32 v[80:81], v[68:69], v[80:81] op_sel:[1,0]
	v_readlane_b32 s25, v253, 52
	v_pk_fma_f32 v[124:125], v[68:69], v[78:79], v[80:81] op_sel_hi:[0,1,1] neg_lo:[0,0,1] neg_hi:[0,0,1]
	v_pk_fma_f32 v[126:127], v[68:69], v[78:79], v[80:81] op_sel_hi:[0,1,1]
	v_pk_mov_b32 v[82:83], v[126:127], v[124:125] op_sel:[1,0]
	v_mov_b32_e32 v80, v124
	v_mov_b32_e32 v81, v127
	v_pk_mul_f32 v[82:83], v[68:69], v[82:83] op_sel:[1,0]
	v_cvt_pk_bf16_f32 v18, v18, v20
	v_xor_b32_e32 v20, 0x80000000, v23
	v_pk_fma_f32 v[128:129], v[68:69], v[80:81], v[82:83] op_sel_hi:[0,1,1] neg_lo:[0,0,1] neg_hi:[0,0,1]
	v_pk_fma_f32 v[130:131], v[68:69], v[80:81], v[82:83] op_sel_hi:[0,1,1]
	v_pk_mov_b32 v[84:85], v[130:131], v[128:129] op_sel:[1,0]
	v_mov_b32_e32 v82, v128
	v_mov_b32_e32 v83, v131
	v_pk_mul_f32 v[84:85], v[70:71], v[84:85] op_sel_hi:[0,1]
	v_pk_fma_f32 v[138:139], v[68:69], v[82:83], v[84:85] op_sel_hi:[0,1,1] neg_lo:[0,0,1] neg_hi:[0,0,1]
	v_pk_fma_f32 v[140:141], v[68:69], v[82:83], v[84:85] op_sel_hi:[0,1,1]
	v_pk_mov_b32 v[86:87], v[140:141], v[138:139] op_sel:[1,0]
	v_mov_b32_e32 v84, v138
	v_mov_b32_e32 v85, v141
	v_pk_mul_f32 v[86:87], v[70:71], v[86:87] op_sel_hi:[0,1]
	v_pk_fma_f32 v[142:143], v[68:69], v[84:85], v[86:87] op_sel_hi:[0,1,1] neg_lo:[0,0,1] neg_hi:[0,0,1]
	v_pk_fma_f32 v[144:145], v[68:69], v[84:85], v[86:87] op_sel_hi:[0,1,1]
	v_pk_mov_b32 v[88:89], v[144:145], v[142:143] op_sel:[1,0]
	v_mov_b32_e32 v86, v142
	v_mov_b32_e32 v87, v145
	v_pk_mul_f32 v[88:89], v[70:71], v[88:89] op_sel_hi:[0,1]
	v_pk_fma_f32 v[146:147], v[68:69], v[86:87], v[88:89] op_sel_hi:[0,1,1] neg_lo:[0,0,1] neg_hi:[0,0,1]
	v_pk_fma_f32 v[160:161], v[68:69], v[86:87], v[88:89] op_sel_hi:[0,1,1]
	v_pk_mov_b32 v[90:91], v[160:161], v[146:147] op_sel:[1,0]
	v_mov_b32_e32 v88, v146
	v_mov_b32_e32 v89, v161
	v_pk_mul_f32 v[90:91], v[70:71], v[90:91] op_sel_hi:[0,1]
	v_pk_fma_f32 v[162:163], v[68:69], v[88:89], v[90:91] op_sel_hi:[0,1,1] neg_lo:[0,0,1] neg_hi:[0,0,1]
	v_pk_fma_f32 v[164:165], v[68:69], v[88:89], v[90:91] op_sel_hi:[0,1,1]
	v_pk_mov_b32 v[92:93], v[164:165], v[162:163] op_sel:[1,0]
	v_mov_b32_e32 v90, v162
	v_mov_b32_e32 v91, v165
	v_pk_mul_f32 v[92:93], v[70:71], v[92:93] op_sel_hi:[0,1]
	v_pk_fma_f32 v[166:167], v[68:69], v[90:91], v[92:93] op_sel_hi:[0,1,1] neg_lo:[0,0,1] neg_hi:[0,0,1]
	v_pk_fma_f32 v[168:169], v[68:69], v[90:91], v[92:93] op_sel_hi:[0,1,1]
	v_mov_b32_e32 v92, v166
	v_mov_b32_e32 v93, v169
	v_pk_mul_f32 v[94:95], v[70:71], v[92:93] op_sel_hi:[0,1]
	v_pk_mov_b32 v[96:97], v[168:169], v[166:167] op_sel:[1,0]
	s_lshl_b32 s0, s25, 9
; #define LAS __attribute__((address_space(3)))
; __device__ __forceinline__ unsigned cvt_pk_bf16(float lo, float hi) { unsigned r; asm("v_cvt_pk_bf16_f32 %0, %1, %2" : "=v"(r) : "v"(lo), "v"(hi)); return r; }
; __device__ __forceinline__ f32x4 ldbf4(const bf16_t* p) { const u32x2 w = *(const u32x2*)p; return (f32x4){bf_lo(w.x), bf_hi(w.x), bf_lo(w.y), bf_hi(w.y)}; }
; template <bool SAMPLE>
; __device__ __forceinline__ void ssm_item(kp_t kp, LAS unsigned char* lds, int l, int item, const bf16_t* Z, float* YM, int tid, int lane, int wave) {
;     ...
;     { float pr = lr, pi = li;
; #pragma unroll
;       for (int tt = 0; tt < 16; ++tt) { pw[tt] = (f32x2){pr, pi}; const float npr = pr * lr - pi * li; pi = pr * li + pi * lr; pr = npr; } }
;     const float l16r = pw[15].x, l16i = pw[15].y;
;     bf16x8 cf[4];
;     {
; #pragma unroll
;       for (int ks = 0; ks < 4; ++ks) { const f32x4 cr = craw[ks], ci = ciraw[ks];
;           u32x4 w; w.x = cvt_pk_bf16(cr[0], -ci[0]); w.y = cvt_pk_bf16(cr[1], -ci[1]); w.z = cvt_pk_bf16(cr[2], -ci[2]); w.w = cvt_pk_bf16(cr[3], -ci[3]);
;           cf[ks] = __builtin_bit_cast(bf16x8, w); } }
;     LAS float* Ub = (LAS float*)lds; LAS f32x2* Eb = (LAS f32x2*)(lds + 16384); LAS unsigned char* Hb = lds + 20480; LAS float* Yb = (LAS float*)(lds + 55296);
;     float car = 0.f, cai = 0.f;
;     constexpr int NCH = SAMPLE ? 1 : 16;
;     for (int ch = 0; ch < NCH; ++ch) {
;         const size_t tok0 = row0 + ch * 128;
;         LAS float* U = Ub + (ch & 1) * 2048;
;         *(LAS f32x4*)(U + tid * 4) = ureg;
;         if (ch < NCH - 1) ureg = ldbf4(zsrc + (size_t)(ch + 1) * 128 * INW);
;         __syncthreads();
;         f32x2 hl[16]; f32x2 h = (f32x2){0.f, 0.f};
; #pragma unroll
;         for (int tt = 0; tt < 16; ++tt) { const LAS f32x4* up = (const LAS f32x4*)(U + (wave * 16 + tt) * 16);
	v_pk_fma_f32 v[98:99], v[68:69], v[96:97], v[94:95] op_sel_hi:[0,1,1]
	v_pk_fma_f32 v[170:171], v[68:69], v[96:97], v[94:95] op_sel_hi:[0,1,1] neg_lo:[0,0,1] neg_hi:[0,0,1]
	v_pk_mov_b32 v[94:95], v[170:171], v[98:99] op_sel:[1,0]
	v_mov_b32_e32 v172, v98
	v_mov_b32_e32 v173, v171
	v_pk_mul_f32 v[96:97], v[70:71], v[94:95] op_sel_hi:[0,1]
	v_pk_fma_f32 v[98:99], v[68:69], v[172:173], v[96:97] op_sel_hi:[0,1,1]
	v_pk_fma_f32 v[174:175], v[68:69], v[172:173], v[96:97] op_sel_hi:[0,1,1] neg_lo:[0,0,1] neg_hi:[0,0,1]
	v_pk_mov_b32 v[96:97], v[174:175], v[98:99] op_sel:[1,0]
	v_mov_b32_e32 v176, v98
	v_mov_b32_e32 v177, v175
	v_pk_mul_f32 v[98:99], v[70:71], v[96:97] op_sel_hi:[0,1]
	v_pk_fma_f32 v[100:101], v[68:69], v[176:177], v[98:99] op_sel_hi:[0,1,1]
	v_pk_fma_f32 v[188:189], v[68:69], v[176:177], v[98:99] op_sel_hi:[0,1,1] neg_lo:[0,0,1] neg_hi:[0,0,1]
	v_pk_mov_b32 v[98:99], v[188:189], v[100:101] op_sel:[1,0]
	v_mov_b32_e32 v190, v100
	v_mov_b32_e32 v191, v189
	v_pk_mul_f32 v[100:101], v[70:71], v[98:99] op_sel_hi:[0,1]
	v_cvt_pk_bf16_f32 v19, v19, v20
	s_add_i32 s0, s0, 0
	v_lshlrev_b32_e32 v20, 3, v110
	v_pk_fma_f32 v[102:103], v[68:69], v[190:191], v[100:101] op_sel_hi:[0,1,1]
	v_pk_fma_f32 v[218:219], v[68:69], v[190:191], v[100:101] op_sel_hi:[0,1,1] neg_lo:[0,0,1] neg_hi:[0,0,1]
	v_add_u32_e32 v217, s0, v20
	s_lshl_b32 s0, s25, 4
	v_pk_mov_b32 v[100:101], v[218:219], v[102:103] op_sel:[1,0]
	v_add_u32_e32 v218, 0, v20
	s_mov_b32 s84, 0xb800
	v_or_b32_e32 v20, s0, v136
	s_movk_i32 s1, 0x110
	v_mul_lo_u32 v20, v20, s1
	s_lshl_b32 s21, s4, 5
	s_lshl_b32 s20, s4, 6
	s_lshl_b32 s24, s25, 10
	s_cmp_lt_u32 s25, 4
	s_cbranch_scc0 .Lssm_prio_done
	s_setprio 1
.Lssm_prio_done:
	v_add_u32_e32 v140, 0, v20
	v_or_b32_e32 v20, s0, v111
	v_readlane_b32 s0, v253, 51
	s_cmp_lt_u32 s0, 64
	s_cselect_b64 s[0:1], -1, 0
	s_cmp_eq_u32 s25, 1
	s_cselect_b64 s[16:17], -1, 0
	s_cmp_eq_u32 s25, 2
	s_cselect_b64 s[4:5], -1, 0
	s_cmp_eq_u32 s25, 3
	s_cselect_b64 s[6:7], -1, 0
	s_cmp_eq_u32 s25, 4
	v_xor_b32_e32 v28, 0x80000000, v28
	s_cselect_b64 s[8:9], -1, 0
	s_cmp_eq_u32 s25, 5
	v_cvt_pk_bf16_f32 v8, v8, v28
	v_xor_b32_e32 v28, 0x80000000, v29
	s_cselect_b64 s[10:11], -1, 0
	s_cmp_eq_u32 s25, 6
	v_cvt_pk_bf16_f32 v9, v9, v28
	v_xor_b32_e32 v28, 0x80000000, v30
	s_cselect_b64 s[12:13], -1, 0
	s_cmp_eq_u32 s25, 7
	s_mul_i32 s27, s2, 0xa00000
	v_cvt_pk_bf16_f32 v10, v10, v28
	v_xor_b32_e32 v28, 0x80000000, v31
	s_cselect_b64 s[14:15], -1, 0
	v_or_b32_e32 v22, 2, v20
	v_or_b32_e32 v23, 3, v20
	s_mul_hi_i32 s26, s2, 0xa00000
	s_or_b32 s21, s27, s21
	v_cvt_pk_bf16_f32 v11, v11, v28
	v_xor_b32_e32 v28, 0x80000000, v115
	v_mov_b32_e32 v115, v142
	v_lshl_or_b32 v223, v22, 4, v136
	v_lshl_or_b32 v225, v23, 4, v136
	v_lshlrev_b32_e32 v142, 6, v22
	v_lshlrev_b32_e32 v144, 6, v23
	v_mov_b32_e32 v22, s21
	v_mov_b32_e32 v23, s26
	v_mov_b32_e32 v220, v102
	v_mov_b32_e32 v221, v219
	v_pk_mul_f32 v[104:105], v[70:71], v[100:101] op_sel_hi:[0,1]
	v_xor_b32_e32 v24, 0x80000000, v24
	v_or_b32_e32 v21, 1, v20
	v_mad_i64_i32 v[22:23], s[26:27], v134, s56, v[22:23]
	v_pk_fma_f32 v[102:103], v[68:69], v[220:221], v[104:105] op_sel_hi:[0,1,1]
	v_pk_fma_f32 v[104:105], v[68:69], v[220:221], v[104:105] op_sel_hi:[0,1,1] neg_lo:[0,0,1] neg_hi:[0,0,1]
	v_xor_b32_e32 v32, 0x80000000, v32
	v_cvt_pk_bf16_f32 v12, v12, v24
	v_xor_b32_e32 v24, 0x80000000, v25
	v_mov_b32_e32 v29, v112
	v_mov_b32_e32 v111, v128
	v_xor_b32_e32 v112, 0x80000000, v141
	v_pk_add_f32 v[128:129], v[220:221], 0 neg_lo:[1,1] neg_hi:[1,1]
	v_lshl_or_b32 v221, v21, 4, v136
	v_lshlrev_b32_e32 v141, 6, v21
	v_and_b32_e32 v21, 3, v133
	v_readlane_b32 s26, v253, 46
	v_cvt_pk_bf16_f32 v4, v4, v32
	v_xor_b32_e32 v32, 0x80000000, v33
	v_cvt_pk_bf16_f32 v13, v13, v24
	v_xor_b32_e32 v24, 0x80000000, v26
	v_lshl_or_b32 v22, v21, 3, v22
	v_readlane_b32 s27, v253, 47
	v_ashrrev_i32_e32 v21, 31, v20
	v_cvt_pk_bf16_f32 v5, v5, v32
	v_xor_b32_e32 v32, 0x80000000, v34
	v_cvt_pk_bf16_f32 v14, v14, v24
	v_xor_b32_e32 v24, 0x80000000, v27
	v_mov_b32_e32 v113, v138
	v_mov_b32_e32 v129, v219
	v_lshl_or_b32 v219, v20, 4, v136
	v_lshlrev_b32_e32 v138, 6, v20
	v_lshl_add_u64 v[134:135], s[26:27], 0, v[22:23]
	s_lshl_b64 s[26:27], s[2:3], 24
	v_lshlrev_b64 v[20:21], 13, v[20:21]
	v_mov_b32_e32 v106, v102
	v_mov_b32_e32 v107, v105
	v_cvt_pk_bf16_f32 v6, v6, v32
	v_xor_b32_e32 v32, 0x80000000, v35
	v_cvt_pk_bf16_f32 v15, v15, v24
	v_lshlrev_b32_e32 v24, 2, v110
	v_lshl_add_u64 v[20:21], s[26:27], 0, v[20:21]
	v_mov_b32_e32 v132, 0
	v_cvt_pk_bf16_f32 v7, v7, v32
	v_xor_b32_e32 v70, 0x80000000, v71
	v_sub_u32_e32 v139, v218, v24
	v_and_b32_e32 v143, 48, v133
	s_mulk_i32 s25, 0x1100
	v_xor_b32_e32 v32, 0x80000000, v123
	v_xor_b32_e32 v34, 0x80000000, v127
	v_mov_b32_e32 v35, v124
	v_xor_b32_e32 v110, 0x80000000, v131
	v_pk_add_f32 v[122:123], v[172:173], 0 neg_lo:[1,1] neg_hi:[1,1]
	v_pk_add_f32 v[124:125], v[176:177], 0 neg_lo:[1,1] neg_hi:[1,1]
	v_pk_add_f32 v[126:127], v[190:191], 0 neg_lo:[1,1] neg_hi:[1,1]
	v_pk_add_f32 v[130:131], v[106:107], 0 neg_lo:[1,1] neg_hi:[1,1]
	v_or3_b32 v20, v20, s20, v148
	s_mov_b32 s23, 0
	s_waitcnt vmcnt(0)
	v_lshlrev_b32_e32 v0, 16, v2
	v_and_b32_e32 v1, 0xffff0000, v2
	v_lshlrev_b32_e32 v2, 16, v3
	v_and_b32_e32 v3, 0xffff0000, v3
	v_mov_b32_e32 v39, v43
	v_mov_b32_e32 v42, v68
	v_mov_b32_e32 v43, v68
	v_pk_mov_b32 v[108:109], v[104:105], v[102:103] op_sel:[1,0]
	v_lshlrev_b32_e32 v25, 4, v133
	v_mov_b32_e32 v26, v70
	v_mov_b32_e32 v27, v68
	v_xor_b32_e32 v30, 0x80000000, v119
	v_mov_b32_e32 v31, v116
	v_mov_b32_e32 v33, v120
	v_xor_b32_e32 v114, 0x80000000, v145
	v_xor_b32_e32 v116, 0x80000000, v161
	v_mov_b32_e32 v117, v146
	v_xor_b32_e32 v118, 0x80000000, v165
	v_mov_b32_e32 v119, v162
	v_xor_b32_e32 v120, 0x80000000, v169
	v_mov_b32_e32 v121, v166
	v_mov_b32_e32 v123, v171
	v_mov_b32_e32 v125, v175
	v_mov_b32_e32 v127, v189
	v_mov_b32_e32 v131, v105
	v_lshl_add_u32 v220, v219, 2, 0
	v_lshl_add_u32 v222, v221, 2, 0
	v_lshl_add_u32 v224, v223, 2, 0
	v_lshl_add_u32 v226, v225, 2, 0
	v_mov_b32_e32 v104, v105
	v_mov_b32_e32 v103, v102
	v_lshl_add_u64 v[136:137], s[62:63], 0, v[20:21]
	s_mov_b64 s[20:21], 0
	v_add_u32_e32 v148, s25, v139
	v_add_u32_e32 v227, v140, v143
	v_add_u32_e32 v228, 0, v138
	v_add_u32_e32 v229, 0, v141
	v_add_u32_e32 v230, 0, v142
	v_add_u32_e32 v231, 0, v144
	v_mov_b32_e32 v133, v132
	s_branch .LBB0_101
